# P0 tail (pads, WukP, rope table) dealt only to workgroups 128..255, which carry one adaLN item instead of two
# baseline (speedup 1.0000x reference)
.LBB0_49:
	v_writelane_b32 v254, s34, 44
	s_nop 1
	v_writelane_b32 v254, s35, 45
	s_or_b64 exec, exec, s[4:5]
	s_ashr_i32 s97, s96, 31
	s_lshl_b64 s[88:89], s[96:97], 9
	s_ashr_i32 s93, s92, 31
	v_lshl_add_u64 v[6:7], s[88:89], 0, v[10:11]
	s_mov_b64 s[0:1], 0xc000
	s_lshl_b64 s[34:35], s[92:93], 9
	v_cmp_gt_u64_e32 vcc, s[0:1], v[6:7]
	s_barrier
	s_mov_b32 s98, s96
	s_mov_b32 s99, s92
	s_cmpk_eq_u32 s92, 0x100
	s_cbranch_scc0 .Lp0m_skip
	s_cmpk_ge_u32 s96, 0x80
	s_cbranch_scc0 .Lp0m_lo
	s_sub_i32 s96, s96, 0x80
	s_movk_i32 s92, 0x80
	s_lshl_b32 s100, s96, 9
	v_add_u32_e32 v6, s100, v10
	v_mov_b32_e32 v7, 0
	s_mov_b64 s[34:35], 0x10000
	s_branch .Lp0m_vcc
.Lp0m_lo:
	v_mov_b32_e32 v6, 0
	v_mov_b32_e32 v7, 1
.Lp0m_vcc:
	v_cmp_gt_u64_e32 vcc, s[0:1], v[6:7]
.Lp0m_skip:
	s_and_saveexec_b64 s[0:1], vcc
	s_cbranch_execz .LBB0_52
	s_lshl_b64 s[2:3], s[96:97], 13
	s_add_u32 s2, s50, s2
	s_addc_u32 s3, s51, s3
	v_lshl_add_u64 v[2:3], v[10:11], 4, s[2:3]
	s_mov_b64 s[2:3], 0x1840000
	v_lshl_add_u64 v[8:9], v[2:3], 0, s[2:3]
	v_mov_b32_e32 v2, 0
	s_lshl_b64 s[4:5], s[92:93], 13
	s_mov_b64 s[6:7], 0
	v_mov_b32_e32 v3, v2
	v_mov_b32_e32 v4, v2
	v_mov_b32_e32 v5, v2
	s_mov_b64 s[12:13], 0xbfff
	v_mov_b64_e32 v[12:13], v[6:7]

.LBB0_69:
	s_or_b64 exec, exec, s[12:13]
	s_mov_b32 s96, s98
	s_mov_b32 s92, s99
	s_lshl_b64 s[34:35], s[92:93], 9
	v_lshrrev_b32_e32 v1, 20, v0
	v_lshrrev_b32_e32 v0, 10, v0
	v_or_b32_e32 v0, v0, v1
	s_movk_i32 s0, 0x3ff
	v_and_or_b32 v0, v0, s0, v250
	v_cmp_eq_u32_e32 vcc, 0, v0
	s_barrier
	s_and_saveexec_b64 s[0:1], vcc
	s_cbranch_execz .LBB0_79
	buffer_wbl2 sc1
	s_waitcnt vmcnt(0)
	s_load_dwordx2 s[4:5], s[8:9], 0x58
	v_mov_b32_e32 v2, 0
	s_mov_b64 s[6:7], exec
	v_mbcnt_lo_u32_b32 v1, s6, 0
	v_mbcnt_hi_u32_b32 v1, s7, v1
	s_waitcnt lgkmcnt(0)
	global_load_dword v0, v2, s[4:5] offset:40
	v_cmp_eq_u32_e32 vcc, 0, v1
	s_and_saveexec_b64 s[8:9], vcc
	s_cbranch_execz .LBB0_72
	s_bcnt1_i32_b64 s2, s[6:7]
	v_mov_b32_e32 v3, s2
	global_atomic_add v3, v2, v3, s[4:5] offset:32 sc0
